# P=80 with KSPLIT 1536
# baseline (speedup 1.0000x reference)
; __global__ void __launch_bounds__(NWAVES * 64, 2) hybrid_fwd(Args A) {
;     ...
;             if (s == 0 && EN(1)) { pg8::Gemm g{WS_PTR(const bf16, WS_HB), WS_PTR(const bf16, WS_WINT) + (size_t)l * DINP * D, M, DINP, D, D}; pg8::StaticOrder S; S.init(M, DINP, C.G, C.bid);
;                 pg8::EpiU E{WS_PTR(bf16, WS_U), WS_PTR(const float, WS_SS) + (size_t)l * M};
;                 pg8::gemm_phase<pg8::EpiU, pg8::StaticOrder, G1_ALIGN, G1_SP2>(C.lds, g, S, E); }
;             else if (s == 1 && EN(2)) phase_prep(A, C, l);
;             else if ((s == 2 && EN(3)) || (s == 3 && EN(4)) || (s == 4 && EN(5))) {
;                 const bool split = C.G >= 192; bool go = (s == 4); int k0 = split ? KSPLIT : 0, kl = D - k0, gg = C.G, cc = C.bid, mrows = M; size_t roff = 0;
;                 if (s == 2) { go = phase_mixers(A, C, l, rep ? DUP_UN : 7); k0 = 0; kl = KSPLIT; gg = C.G - 128; cc = C.bid - 128; mrows = MP; }
;                 if (s == 3) { phase_post(A, C, l, split ? 8 : 0); go = split && C.bid < 8 && !rep; k0 = 0; kl = KSPLIT; gg = 8; cc = C.bid; mrows = MS; roff = (size_t)MP * D; }
;                 if (go) { pg8::Gemm g{WS_PTR(const bf16, WS_XN) + roff + k0, WS_PTR(const bf16, WS_WOUTT) + (size_t)l * D * D + k0, mrows, D, kl, D}; pg8::StaticOrder S; S.init(mrows, D, gg, cc);
;                     const bool first = (l == 0) && (s != 4 || !split);
;                     float* Hout = ((rep && s == 4) ? WS_PTR(float, WS_U) : A.out) + roff;
;                     pg8::EpiResN E{Hout, first ? (s == 3 ? A.in[I_XS] : A.in[I_XP]) : Hout, first ? A.in[I_XS] - (size_t)MP * D : Hout, WS_PTR(bf16, WS_HB), WS_PTR(float, WS_SS) + (size_t)(l + 1) * M, s == 4 && !rep};
;                     pg8::gemm_phase<pg8::EpiResN, pg8::StaticOrder, G2_ALIGN, true>(C.lds, g, S, E); }
.LBB0_14:
	v_readlane_b32 s12, v253, 0
	s_cmpk_lt_i32 s12, 0xb16
	s_cselect_b64 s[2:3], -1, 0
	v_writelane_b32 v253, s2, 11
	s_load_dword s13, s[0:1], 0xe8
	s_load_dwordx4 s[16:19], s[0:1], 0xc0
	s_load_dwordx2 s[14:15], s[0:1], 0xd0
	v_writelane_b32 v253, s3, 12
	s_ashr_i32 s2, s12, 31
	v_writelane_b32 v253, s2, 13
	s_lshr_b32 s2, s2, 29
	s_add_i32 s2, s12, s2
	s_ashr_i32 s9, s2, 3
	s_and_b32 s2, s2, -8
	s_sub_i32 s10, s12, s2
	s_mul_i32 s2, s10, 0x162
	s_add_i32 s11, s2, 6
	s_waitcnt lgkmcnt(0)
	s_ashr_i32 s2, s13, 31
	s_cmpk_lt_i32 s13, 0xc0
	v_writelane_b32 v253, s2, 14
	s_cselect_b64 s[2:3], -1, 0
	v_writelane_b32 v253, s2, 15
	s_cmpk_gt_i32 s13, 0xbf
	s_load_dwordx16 s[80:95], s[0:1], 0x0
	v_writelane_b32 v253, s3, 16
	s_cselect_b64 s[2:3], -1, 0
	s_and_b64 s[6:7], s[2:3], exec
	s_cselect_b32 s7, 8, 0
	s_cselect_b32 s6, 0x600, 0
	v_writelane_b32 v253, s7, 17
	v_writelane_b32 v253, s6, 18
	s_sub_i32 s6, 0x800, s6
	v_writelane_b32 v253, s6, 19
	s_add_u32 s6, s18, 0x10692000
	v_writelane_b32 v253, s6, 20
	s_addc_u32 s6, s19, 0
	v_writelane_b32 v253, s6, 21
	s_add_u32 s6, s18, 0x10200000
	v_writelane_b32 v253, s6, 22
	s_addc_u32 s6, s19, 0
	v_writelane_b32 v253, s6, 23
	s_add_u32 s6, s18, 0x10bb6000
	v_writelane_b32 v253, s6, 24
	s_addc_u32 s6, s19, 0
	v_writelane_b32 v253, s6, 25
	s_add_u32 s6, s18, 0x10492000
	v_writelane_b32 v253, s6, 26
	s_addc_u32 s6, s19, 0
	s_waitcnt lgkmcnt(0)
	s_cmp_eq_u64 s[92:93], 0
	v_writelane_b32 v253, s6, 27
	s_cselect_b64 s[6:7], -1, 0
	v_writelane_b32 v253, s6, 28
	s_cmp_lg_u64 s[92:93], 0
	s_load_dwordx16 s[36:51], s[0:1], 0x40
	v_writelane_b32 v253, s7, 29
	s_cselect_b64 s[6:7], -1, 0
	v_writelane_b32 v253, s6, 30
	v_mov_b32_e32 v207, 0x260
	v_mov_b32_e32 v229, 0x3727c5ac
	v_writelane_b32 v253, s7, 31
	s_add_u32 s6, s14, 0x8000
	v_writelane_b32 v253, s6, 32
	s_addc_u32 s6, s15, 0
	v_writelane_b32 v253, s6, 33
	s_add_i32 s6, s13, 0xffffff80
	v_writelane_b32 v253, s6, 34
	s_add_i32 s6, s12, 0xffffff80
	s_cmp_lt_i32 s12, 8
	v_writelane_b32 v253, s6, 35
	s_cselect_b64 s[6:7], -1, 0
	s_and_b64 s[2:3], s[6:7], s[2:3]
	v_writelane_b32 v253, s2, 36
	v_mov_b32_e32 v252, 1
	v_mov_b32_e32 v251, 0x7f800000
	v_writelane_b32 v253, s3, 37
	s_add_u32 s2, s82, 0xf0000000
	v_writelane_b32 v253, s2, 38
	s_addc_u32 s2, s83, -1
	s_cmp_lg_u64 s[94:95], 0
	v_writelane_b32 v253, s2, 39
	s_cselect_b64 s[2:3], -1, 0
	v_writelane_b32 v253, s2, 40
	s_cmp_lg_u32 s26, 2
	v_mov_b32_e32 v142, 0x41b17218
	v_writelane_b32 v253, s3, 41
	s_cselect_b64 s[2:3], -1, 0
	v_writelane_b32 v253, s2, 42
	v_mov_b32_e32 v143, 0x3000
	s_movk_i32 s33, 0x7fff
	v_writelane_b32 v253, s3, 43
	s_add_u32 s2, s14, 0x4200
	s_addc_u32 s3, s15, 0
	v_writelane_b32 v253, s2, 44
	s_mov_b32 s96, 0xffff0000
	s_mov_b32 s97, 0x3fb8aa3b
	v_writelane_b32 v253, s3, 45
	s_add_u32 s2, s14, 0x4400
	s_addc_u32 s3, s15, 0
	v_writelane_b32 v253, s2, 46
	s_mov_b32 s20, 0xbfb8aa3b
	s_mov_b32 s21, 0xb2a5705f
	v_writelane_b32 v253, s3, 47
	s_add_u32 s2, s14, 0x4500
	s_addc_u32 s3, s15, 0
	v_writelane_b32 v253, s2, 48
	s_mov_b32 s28, 0x42ce8ed0
	s_mov_b32 s29, 0xc2b17218
	v_writelane_b32 v253, s3, 49
	s_add_u32 s2, s14, 0x4600
	s_addc_u32 s3, s15, 0
	v_writelane_b32 v253, s2, 50
	s_mov_b32 s34, 0x7f800000
	s_mov_b32 s35, 0x800000
	v_writelane_b32 v253, s3, 51
	s_add_u32 s2, s14, 0x4700
	s_addc_u32 s3, s15, 0
	v_writelane_b32 v253, s2, 52
	s_mov_b64 s[22:23], 0x80
	s_nop 0
	v_writelane_b32 v253, s3, 53
	s_add_u32 s2, s14, 0x4800
	s_addc_u32 s3, s15, 0
	v_writelane_b32 v253, s2, 54
	s_nop 1
	v_writelane_b32 v253, s3, 55
	s_add_u32 s2, s14, 0x4900
	s_addc_u32 s3, s15, 0
	v_writelane_b32 v253, s2, 56
	s_nop 1
	v_writelane_b32 v253, s3, 57
	s_add_u32 s2, s14, 0x4a00
	s_addc_u32 s3, s15, 0
	v_writelane_b32 v253, s2, 58
	s_nop 1
	v_writelane_b32 v253, s3, 59
	s_add_u32 s2, s14, 0x4b00
	s_addc_u32 s3, s15, 0
	v_writelane_b32 v253, s2, 60
	s_nop 1
	v_writelane_b32 v253, s3, 61
	s_add_u32 s2, s14, 0x4c00
	s_addc_u32 s3, s15, 0
	v_writelane_b32 v253, s2, 62
	s_nop 1
	v_writelane_b32 v253, s3, 63
	s_add_u32 s2, s14, 0x4d00
	s_addc_u32 s3, s15, 0
	v_writelane_b32 v254, s2, 0
	s_nop 1
	v_writelane_b32 v254, s3, 1
	s_add_u32 s2, s14, 0x4e00
	s_addc_u32 s3, s15, 0
	v_writelane_b32 v254, s2, 2
	s_nop 1
	v_writelane_b32 v254, s3, 3
	s_add_u32 s2, s14, 0x4f00
	s_addc_u32 s3, s15, 0
	v_writelane_b32 v254, s2, 4
	s_nop 1
	v_writelane_b32 v254, s3, 5
	s_add_u32 s2, s14, 0x5000
	s_addc_u32 s3, s15, 0
	v_writelane_b32 v254, s2, 6
	s_nop 1
	v_writelane_b32 v254, s3, 7
	s_add_u32 s2, s14, 0x5100
	s_addc_u32 s3, s15, 0
	v_writelane_b32 v254, s2, 8
	s_nop 1
	v_writelane_b32 v254, s3, 9
	s_add_u32 s2, s14, 0x5200
	s_addc_u32 s3, s15, 0
	v_writelane_b32 v254, s2, 10
	s_nop 1
	v_writelane_b32 v254, s3, 11
	s_add_u32 s2, s14, 0x5300
	s_addc_u32 s3, s15, 0
	v_writelane_b32 v254, s2, 12
	s_cmp_eq_u32 s8, 15
	s_nop 0
	v_writelane_b32 v254, s3, 13
	s_cselect_b64 s[2:3], -1, 0
	v_writelane_b32 v254, s2, 14
	s_cmp_eq_u32 s8, 14
	s_nop 0
	v_writelane_b32 v254, s3, 15
	s_cselect_b64 s[2:3], -1, 0
	v_writelane_b32 v254, s2, 16
	s_cmp_eq_u32 s8, 13
	s_nop 0
	v_writelane_b32 v254, s3, 17
	s_cselect_b64 s[2:3], -1, 0
	v_writelane_b32 v254, s2, 18
; __device__ __forceinline__ unsigned xb_ld(unsigned* p)              { return __hip_atomic_load(p, __ATOMIC_RELAXED, __HIP_MEMORY_SCOPE_AGENT); }
;     __host__ __device__ bool next(int i, Unit& u) const {
;         const long L = (long)i * G + c; if (L >= nwg) return false;
;         int wgid = (int)L; { const int q = nwg / NXCD, r = nwg % NXCD, xcd = wgid % NXCD, off = wgid / NXCD; wgid = (xcd < r ? xcd * (q + 1) : r * (q + 1) + (xcd - r) * q) + off; }
;         const int nig = WGM * nN, gid = wgid / nig, fm = gid * WGM, gsz = (nM - fm) < WGM ? (nM - fm) : WGM;
;         u.pm = fm + ((wgid % nig) % gsz); u.pn = (wgid % nig) / gsz; return true;
; __device__ __forceinline__ void xcd_barrier_complete(unsigned* bar, unsigned x, unsigned& nloc, unsigned& nx) {
;     const unsigned G = gridDim.x * gridDim.y * gridDim.z;
;     unsigned sum, cnt, mine, sp = 0u;
;     for (;;) {
;         sum = 0u; cnt = 0u; mine = 0u;
; #pragma unroll
;         for (unsigned j = 0; j < 16; ++j) { const unsigned c = xb_ld(&bar[XB_XCNT(j)]); sum += c; cnt += (c > 0u) ? 1u : 0u; mine = (j == x) ? c : mine; }
;         if (sum == G) break;
;         __builtin_amdgcn_s_sleep(1);
;         if ((++sp & 255u) == 0u) { if (xb_ld(&bar[XB_TMO])) break; if (sp > XB_SPIN_CAP) { atomicAdd(&bar[XB_TMO], 1u); break; } }
;     }
;     nloc = mine > 0u ? mine : 1u; nx = cnt > 0u ? cnt : 1u;
	s_cmp_eq_u32 s8, 12
	s_nop 0
	v_writelane_b32 v254, s3, 19
	s_cselect_b64 s[2:3], -1, 0
	v_writelane_b32 v254, s2, 20
	s_cmp_eq_u32 s8, 11
	s_nop 0
	v_writelane_b32 v254, s3, 21
	s_cselect_b64 s[2:3], -1, 0
	v_writelane_b32 v254, s2, 22
	s_cmp_eq_u32 s8, 10
	s_nop 0
	v_writelane_b32 v254, s3, 23
	s_cselect_b64 s[2:3], -1, 0
	v_writelane_b32 v254, s2, 24
	s_cmp_eq_u32 s8, 9
	s_nop 0
	v_writelane_b32 v254, s3, 25
	s_cselect_b64 s[2:3], -1, 0
	v_writelane_b32 v254, s2, 26
	s_cmp_eq_u32 s8, 8
	s_nop 0
	v_writelane_b32 v254, s3, 27
	s_cselect_b64 s[2:3], -1, 0
	v_writelane_b32 v254, s2, 28
	s_cmp_eq_u32 s8, 7
	s_nop 0
	v_writelane_b32 v254, s3, 29
	s_cselect_b64 s[2:3], -1, 0
	v_writelane_b32 v254, s2, 30
	s_cmp_eq_u32 s8, 6
	s_nop 0
	v_writelane_b32 v254, s3, 31
	s_cselect_b64 s[2:3], -1, 0
	v_writelane_b32 v254, s2, 32
	s_cmp_eq_u32 s8, 5
	s_nop 0
	v_writelane_b32 v254, s3, 33
	s_cselect_b64 s[2:3], -1, 0
	v_writelane_b32 v254, s2, 34
	s_cmp_eq_u32 s8, 4
	s_nop 0
	v_writelane_b32 v254, s3, 35
	s_cselect_b64 s[2:3], -1, 0
	v_writelane_b32 v254, s2, 36
	s_cmp_eq_u32 s8, 3
	s_nop 0
	v_writelane_b32 v254, s3, 37
	s_cselect_b64 s[2:3], -1, 0
	v_writelane_b32 v254, s2, 38
	s_cmp_eq_u32 s8, 2
	s_nop 0
	v_writelane_b32 v254, s3, 39
	s_cselect_b64 s[2:3], -1, 0
	v_writelane_b32 v254, s2, 40
	s_cmp_eq_u32 s8, 1
	s_nop 0
	v_writelane_b32 v254, s3, 41
	s_cselect_b64 s[2:3], -1, 0
	v_writelane_b32 v254, s2, 42
	s_cmp_eq_u32 s8, 0
	s_nop 0
	v_writelane_b32 v254, s3, 43
	s_cselect_b64 s[2:3], -1, 0
	v_writelane_b32 v254, s2, 44
	s_nop 1
	v_writelane_b32 v254, s3, 45
	s_lshl_b32 s2, s8, 8
	s_add_u32 s2, s4, s2
	s_addc_u32 s3, s5, 0
	s_add_u32 s4, s2, 0x1400
	s_addc_u32 s5, s3, 0
	v_writelane_b32 v254, s4, 46
	s_add_u32 s2, s2, 0x2400
	s_addc_u32 s3, s3, 0
	v_writelane_b32 v254, s5, 47
	v_writelane_b32 v254, s2, 48
	s_nop 1
	v_writelane_b32 v254, s3, 49
	s_add_u32 s2, s14, 0x7400
	s_addc_u32 s3, s15, 0
	v_writelane_b32 v254, s2, 50
	s_nop 1
	v_writelane_b32 v254, s3, 51
	s_add_u32 s2, s14, 0x7500
	s_addc_u32 s3, s15, 0
	v_writelane_b32 v254, s2, 52
	s_cmp_lt_i32 s10, 6
	s_mulk_i32 s10, 0x163
	v_writelane_b32 v254, s3, 53
	s_cselect_b32 s2, s10, s11
	s_add_i32 s2, s2, s9
	s_mul_hi_i32 s3, s2, 0x2e8ba2e9
	s_lshr_b32 s4, s3, 31
	s_ashr_i32 s3, s3, 5
	s_add_i32 s3, s3, s4
	s_mul_i32 s4, s3, 0xb0
	s_lshl_b32 s5, s3, 3
	s_sub_i32 s4, s2, s4
	s_sub_i32 s2, 0x81, s5
	s_min_u32 s6, s2, 8
	v_cvt_f32_ubyte0_e32 v2, s6
	v_cvt_f32_i32_e32 v1, s4
	v_rcp_iflag_f32_e32 v3, v2
	s_ashr_i32 s2, s4, 30
	s_or_b32 s7, s2, 1
	v_mul_f32_e32 v3, v1, v3
	v_trunc_f32_e32 v3, v3
	v_fma_f32 v1, -v3, v2, v1
	v_cmp_ge_f32_e64 s[2:3], |v1|, v2
	v_lshrrev_b32_e32 v1, 20, v0
	v_lshrrev_b32_e32 v0, 10, v0
	v_or_b32_e32 v0, v0, v1
	v_cvt_i32_f32_e32 v1, v3
	s_and_b64 s[2:3], s[2:3], exec
	s_movk_i32 s2, 0x3ff
	v_and_or_b32 v0, v0, s2, v185
	s_cselect_b32 s2, s7, 0
	v_readfirstlane_b32 s3, v1
	s_add_i32 s2, s3, s2
	s_mul_i32 s3, s2, s6
	s_sub_i32 s3, s4, s3
	s_sext_i32_i16 s3, s3
	s_add_i32 s3, s5, s3
	v_writelane_b32 v254, s3, 54
	s_sext_i32_i16 s2, s2
	v_writelane_b32 v254, s2, 55
	s_add_u32 s2, s14, 0xfc54300
	s_addc_u32 s3, s15, 0
	v_writelane_b32 v254, s2, 56
	v_mov_b32_e32 v1, 0
	v_mov_b32_e32 v98, v1
	v_writelane_b32 v254, s3, 57
	s_add_u32 s2, s14, 0xfc3c000
	v_writelane_b32 v254, s2, 58
	s_addc_u32 s2, s15, 0
	v_writelane_b32 v254, s2, 59
	s_add_i32 s2, 0, 0xd000
	v_writelane_b32 v254, s2, 60
	s_add_i32 s2, 0, 0x3cf0
	v_writelane_b32 v254, s2, 61
	s_mov_b32 s3, 0
	v_writelane_b32 v254, s2, 62
	v_mov_b32_e32 v99, v1
	v_mov_b32_e32 v100, v1
	v_writelane_b32 v254, s3, 63
	v_cmp_eq_u32_e64 s[2:3], 0, v185
	v_mov_b32_e32 v101, v1
	s_mov_b32 s4, 0x3f317217
	v_writelane_b32 v255, s2, 0
	s_mov_b32 s5, 0xc2ce8ed0
	s_mov_b32 s6, 0x42b17218
	v_writelane_b32 v255, s3, 1
	v_cmp_eq_u32_e64 s[2:3], 0, v0
	s_mov_b32 s7, 0xf800000
	s_nop 0
	v_writelane_b32 v255, s2, 2
	s_nop 1
	v_writelane_b32 v255, s3, 3
	s_waitcnt lgkmcnt(0)
	v_writelane_b32 v255, s36, 4
	s_nop 1
	v_writelane_b32 v255, s37, 5
	v_writelane_b32 v255, s38, 6
	v_writelane_b32 v255, s39, 7
	v_writelane_b32 v255, s40, 8
	v_writelane_b32 v255, s41, 9
	v_writelane_b32 v255, s42, 10
	v_writelane_b32 v255, s43, 11
	v_writelane_b32 v255, s44, 12
	v_writelane_b32 v255, s45, 13
	v_writelane_b32 v255, s46, 14
	v_writelane_b32 v255, s47, 15
	v_writelane_b32 v255, s48, 16
	v_writelane_b32 v255, s49, 17
	v_writelane_b32 v255, s50, 18
	v_writelane_b32 v255, s51, 19
	s_load_dwordx16 s[36:51], s[0:1], 0x80
	s_waitcnt lgkmcnt(0)
	v_writelane_b32 v255, s36, 20
	s_nop 1
	v_writelane_b32 v255, s37, 21
	v_writelane_b32 v255, s38, 22
	v_writelane_b32 v255, s39, 23
	v_writelane_b32 v255, s40, 24
	v_writelane_b32 v255, s41, 25
	v_writelane_b32 v255, s42, 26
	v_writelane_b32 v255, s43, 27
	v_writelane_b32 v255, s44, 28
	v_writelane_b32 v255, s45, 29
	v_writelane_b32 v255, s46, 30
	v_writelane_b32 v255, s47, 31
	v_writelane_b32 v255, s48, 32
	v_writelane_b32 v255, s49, 33
	v_writelane_b32 v255, s50, 34
	v_writelane_b32 v255, s51, 35
	s_mov_b32 s98, 0
	v_writelane_b32 v255, s98, 61
	v_writelane_b32 v255, s98, 62
	v_writelane_b32 v255, s98, 63
	s_branch .LBB0_19

; __global__ void __launch_bounds__(NWAVES * 64, 2) hybrid_fwd(Args A) {
;     ...
;                 if (s == 2) { go = phase_mixers(A, C, l, rep ? DUP_UN : 7); k0 = 0; kl = KSPLIT; gg = C.G - 128; cc = C.bid - 128; mrows = MP; }
;                 if (s == 3) { phase_post(A, C, l, split ? 8 : 0); go = split && C.bid < 8 && !rep; k0 = 0; kl = KSPLIT; gg = 8; cc = C.bid; mrows = MS; roff = (size_t)MP * D; }
;                 if (go) { pg8::Gemm g{WS_PTR(const bf16, WS_XN) + roff + k0, WS_PTR(const bf16, WS_WOUTT) + (size_t)l * D * D + k0, mrows, D, kl, D}; pg8::StaticOrder S; S.init(mrows, D, gg, cc);
.LBB0_1181:
.LBB0_1182:
	s_mov_b32 s8, 0
	s_movk_i32 s3, 0x600
	s_movk_i32 s11, 0x50
	v_readlane_b32 s30, v253, 35
	v_readlane_b32 s17, v253, 34

; __global__ void __launch_bounds__(NWAVES * 64, 2) hybrid_fwd(Args A) {
;     ...
;                 if (s == 3) { phase_post(A, C, l, split ? 8 : 0); go = split && C.bid < 8 && !rep; k0 = 0; kl = KSPLIT; gg = 8; cc = C.bid; mrows = MS; roff = (size_t)MP * D; }
;                 if (go) { pg8::Gemm g{WS_PTR(const bf16, WS_XN) + roff + k0, WS_PTR(const bf16, WS_WOUTT) + (size_t)l * D * D + k0, mrows, D, kl, D}; pg8::StaticOrder S; S.init(mrows, D, gg, cc);
.LBB0_1188:
	v_readlane_b32 s52, v253, 36
	s_mov_b32 s8, 0
	s_movk_i32 s3, 0x600
	s_mov_b32 s17, 8
	s_mov_b32 s11, 1
	s_mov_b64 s[40:41], 0x4000000
	v_readlane_b32 s30, v253, 0
	v_readlane_b32 s53, v253, 37
